# conv item: the 30 look-back rows' GLU inputs fetched as one batch of 60 loads (was 30 serialized load-wait-use round trips behind per-row branches)
# baseline (speedup 1.0000x reference)
; __device__ __forceinline__ float bf2f(unsigned short b) { return __uint_as_float((unsigned)b << 16); }
; __device__ __forceinline__ float sigmoidf_(float x) { return frcp(1.0f + fexp2(-1.4426950408889634f * x)); }
; __device__ __forceinline__ void conv_item(LAS unsigned char* lds, const bf16* PROJ, bf16* MIX, const float* cw, const float* cb, const float* lg, const float* lb, int item, int tid) {
;     ...
;     const int row0 = 32 * item, pos0 = row0 & (SEQ - 1);
;     float w[31];
; #pragma unroll
;     for (int k = 0; k < 31; ++k) w[k] = cw[k * 512 + c];
;     float hw[62];
; #pragma unroll
;     for (int i = 0; i < 62; ++i) { float hv = 0.f;
;         if (pos0 - 30 + i >= 0) { const bf16* rp = PROJ + (size_t)(row0 - 30 + i) * NPROJ; const float a = bf2f(rp[1536 + c]), g = bf2f(rp[2048 + c]); hv = a * sigmoidf_(g); }
;         hw[i] = hv; }
.LBB0_367:
	s_andn2_b64 vcc, exec, s[0:1]
	s_cbranch_vccnz .LBB0_320
	s_cmpk_gt_i32 s24, 0x1ff
	s_mov_b64 s[0:1], -1
	s_cbranch_scc0 .LBB0_441
	s_load_dwordx8 s[16:23], s[78:79], 0x38
	v_readlane_b32 s0, v255, 25
	v_readlane_b32 s1, v255, 24
	v_ashrrev_i32_e32 v201, 31, v200
	v_mov_b32_e32 v90, 0
	s_waitcnt lgkmcnt(0)
	s_add_u32 s0, s16, s0
	s_addc_u32 s1, s17, s1
	v_lshl_add_u64 v[2:3], v[200:201], 2, s[0:1]
	v_add_co_u32_e32 v4, vcc, 0x1000, v2
	s_movk_i32 s0, 0x6000
	s_nop 0
	v_addc_co_u32_e32 v5, vcc, 0, v3, vcc
	v_add_co_u32_e32 v12, vcc, 0x2000, v2
	s_add_i32 s2, s24, 0xfffffe00
	s_nop 0
	v_addc_co_u32_e32 v13, vcc, 0, v3, vcc
	v_add_co_u32_e32 v14, vcc, 0x3000, v2
	s_and_b32 s3, s24, 63
	s_nop 0
	v_addc_co_u32_e32 v15, vcc, 0, v3, vcc
	global_load_dword v10, v[2:3], off
	global_load_dword v9, v[2:3], off offset:2048
	global_load_dword v8, v[4:5], off
	global_load_dword v7, v[4:5], off offset:2048
	s_nop 0
	global_load_dword v5, v[12:13], off
	global_load_dword v0, v[12:13], off offset:2048
	global_load_dword v6, v[14:15], off
	global_load_dword v4, v[14:15], off offset:2048
	v_add_co_u32_e32 v12, vcc, 0x4000, v2
	s_cmp_lg_u32 s3, 0
	s_nop 0
	v_addc_co_u32_e32 v13, vcc, 0, v3, vcc
	v_add_co_u32_e32 v14, vcc, s35, v2
	s_mul_i32 s82, s2, 0x14000
	s_nop 0
	v_addc_co_u32_e32 v15, vcc, 0, v3, vcc
	v_add_co_u32_e32 v28, vcc, s0, v2
	s_cselect_b64 s[0:1], -1, 0
	s_nop 0
	v_addc_co_u32_e32 v29, vcc, 0, v3, vcc
	v_add_co_u32_e32 v20, vcc, 0x7000, v2
	s_cmp_eq_u32 s3, 0
	s_nop 0
	v_addc_co_u32_e32 v21, vcc, 0, v3, vcc
	v_add_co_u32_e32 v22, vcc, s37, v2
	v_mov_b32_e32 v93, 0
	s_nop 0
	v_addc_co_u32_e32 v23, vcc, 0, v3, vcc
	v_add_co_u32_e32 v24, vcc, 0x9000, v2
	s_nop 1
	v_addc_co_u32_e32 v25, vcc, 0, v3, vcc
	global_load_dword v18, v[12:13], off
	global_load_dword v17, v[12:13], off offset:2048
	global_load_dword v16, v[14:15], off offset:2048
	s_nop 0
	global_load_dword v15, v[20:21], off
	global_load_dword v14, v[20:21], off offset:2048
	global_load_dword v12, v[22:23], off
	global_load_dword v11, v[22:23], off offset:2048
	global_load_dword v13, v[24:25], off
	v_add_co_u32_e32 v20, vcc, s38, v2
	s_nop 1
	v_addc_co_u32_e32 v21, vcc, 0, v3, vcc
	v_add_co_u32_e32 v34, vcc, s51, v2
	s_nop 1
	v_addc_co_u32_e32 v35, vcc, 0, v3, vcc
	v_add_co_u32_e32 v22, vcc, s39, v2
	s_nop 1
	v_addc_co_u32_e32 v23, vcc, 0, v3, vcc
	v_add_co_u32_e32 v30, vcc, 0xd000, v2
	s_nop 1
	v_addc_co_u32_e32 v31, vcc, 0, v3, vcc
	v_add_co_u32_e32 v32, vcc, s42, v2
	s_nop 1
	v_addc_co_u32_e32 v33, vcc, 0, v3, vcc
	global_load_dword v26, v[24:25], off offset:2048
	s_nop 0
	global_load_dword v25, v[20:21], off offset:2048
	global_load_dword v24, v[22:23], off
	s_nop 0
	global_load_dword v23, v[22:23], off offset:2048
	s_nop 0
	global_load_dword v21, v[30:31], off
	global_load_dword v19, v[30:31], off offset:2048
	global_load_dword v22, v[32:33], off
	global_load_dword v20, v[32:33], off offset:2048
	v_add_co_u32_e32 v2, vcc, 0xf000, v2
	s_nop 1
	v_addc_co_u32_e32 v3, vcc, 0, v3, vcc
	global_load_dword v33, v[28:29], off offset:-4096
	global_load_dword v32, v[28:29], off
	global_load_dword v31, v[28:29], off offset:2048
	global_load_dword v30, v[34:35], off offset:-4096
	s_nop 0
	global_load_dword v29, v[34:35], off
	global_load_dword v28, v[34:35], off offset:2048
	global_load_dword v27, v[2:3], off
	v_lshl_add_u64 v[2:3], v[200:201], 1, s[84:85]
	s_mov_b64 s[100:101], 0x1400
	v_lshl_add_u64 v[34:35], s[82:83], 1, v[2:3]
	v_add_co_u32_e32 v36, vcc, 0xfffdb400, v34
	s_nop 1
	v_addc_co_u32_e32 v37, vcc, -1, v35, vcc
	global_load_ushort v100, v[36:37], off offset:1024
	global_load_ushort v101, v[36:37], off
	v_lshl_add_u64 v[36:37], v[36:37], 0, s[100:101]
	global_load_ushort v102, v[36:37], off offset:1024
	global_load_ushort v103, v[36:37], off
	v_lshl_add_u64 v[36:37], v[36:37], 0, s[100:101]
	global_load_ushort v104, v[36:37], off offset:1024
	global_load_ushort v105, v[36:37], off
	v_lshl_add_u64 v[36:37], v[36:37], 0, s[100:101]
	global_load_ushort v107, v[36:37], off offset:1024
	global_load_ushort v106, v[36:37], off
	v_lshl_add_u64 v[36:37], v[36:37], 0, s[100:101]
	global_load_ushort v108, v[36:37], off offset:1024
	global_load_ushort v109, v[36:37], off
	v_lshl_add_u64 v[36:37], v[36:37], 0, s[100:101]
	global_load_ushort v110, v[36:37], off offset:1024
	global_load_ushort v111, v[36:37], off
	v_lshl_add_u64 v[36:37], v[36:37], 0, s[100:101]
	global_load_ushort v112, v[36:37], off offset:1024
	global_load_ushort v113, v[36:37], off
	v_lshl_add_u64 v[36:37], v[36:37], 0, s[100:101]
	global_load_ushort v115, v[36:37], off offset:1024
	global_load_ushort v114, v[36:37], off
	v_lshl_add_u64 v[36:37], v[36:37], 0, s[100:101]
	global_load_ushort v116, v[36:37], off offset:1024
	global_load_ushort v117, v[36:37], off
	v_lshl_add_u64 v[36:37], v[36:37], 0, s[100:101]
	global_load_ushort v118, v[36:37], off offset:1024
	global_load_ushort v119, v[36:37], off
	v_lshl_add_u64 v[36:37], v[36:37], 0, s[100:101]
	global_load_ushort v120, v[36:37], off offset:1024
	global_load_ushort v121, v[36:37], off
	v_lshl_add_u64 v[36:37], v[36:37], 0, s[100:101]
	global_load_ushort v123, v[36:37], off offset:1024
	global_load_ushort v122, v[36:37], off
	v_lshl_add_u64 v[36:37], v[36:37], 0, s[100:101]
	global_load_ushort v124, v[36:37], off offset:1024
	global_load_ushort v125, v[36:37], off
	v_lshl_add_u64 v[36:37], v[36:37], 0, s[100:101]
	global_load_ushort v126, v[36:37], off offset:1024
	global_load_ushort v127, v[36:37], off
	v_lshl_add_u64 v[36:37], v[36:37], 0, s[100:101]
	global_load_ushort v128, v[36:37], off offset:1024
	global_load_ushort v129, v[36:37], off
; __device__ __forceinline__ float bf2f(unsigned short b) { return __uint_as_float((unsigned)b << 16); }
; __device__ __forceinline__ float fexp2(float x) { return __builtin_amdgcn_exp2f(x); }
; __device__ __forceinline__ float frcp(float x) { return __builtin_amdgcn_rcpf(x); }
; __device__ __forceinline__ float sigmoidf_(float x) { return frcp(1.0f + fexp2(-1.4426950408889634f * x)); }
; __device__ __forceinline__ void conv_item(LAS unsigned char* lds, const bf16* PROJ, bf16* MIX, const float* cw, const float* cb, const float* lg, const float* lb, int item, int tid) {
;     ...
;     for (int i = 0; i < 62; ++i) { float hv = 0.f;
;         if (pos0 - 30 + i >= 0) { const bf16* rp = PROJ + (size_t)(row0 - 30 + i) * NPROJ; const float a = bf2f(rp[1536 + c]), g = bf2f(rp[2048 + c]); hv = a * sigmoidf_(g); }
;         hw[i] = hv; }
	v_lshl_add_u64 v[36:37], v[36:37], 0, s[100:101]
	global_load_ushort v131, v[36:37], off offset:1024
	global_load_ushort v130, v[36:37], off
	v_lshl_add_u64 v[36:37], v[36:37], 0, s[100:101]
	global_load_ushort v132, v[36:37], off offset:1024
	global_load_ushort v133, v[36:37], off
	v_lshl_add_u64 v[36:37], v[36:37], 0, s[100:101]
	global_load_ushort v134, v[36:37], off offset:1024
	global_load_ushort v135, v[36:37], off
	v_lshl_add_u64 v[36:37], v[36:37], 0, s[100:101]
	global_load_ushort v136, v[36:37], off offset:1024
	global_load_ushort v137, v[36:37], off
	v_lshl_add_u64 v[36:37], v[36:37], 0, s[100:101]
	global_load_ushort v139, v[36:37], off offset:1024
	global_load_ushort v138, v[36:37], off
	v_lshl_add_u64 v[36:37], v[36:37], 0, s[100:101]
	global_load_ushort v140, v[36:37], off offset:1024
	global_load_ushort v141, v[36:37], off
	v_lshl_add_u64 v[36:37], v[36:37], 0, s[100:101]
	global_load_ushort v142, v[36:37], off offset:1024
	global_load_ushort v143, v[36:37], off
	v_lshl_add_u64 v[36:37], v[36:37], 0, s[100:101]
	global_load_ushort v144, v[36:37], off offset:1024
	global_load_ushort v145, v[36:37], off
	v_lshl_add_u64 v[36:37], v[36:37], 0, s[100:101]
	global_load_ushort v147, v[36:37], off offset:1024
	global_load_ushort v146, v[36:37], off
	v_lshl_add_u64 v[36:37], v[36:37], 0, s[100:101]
	global_load_ushort v148, v[36:37], off offset:1024
	global_load_ushort v149, v[36:37], off
	v_lshl_add_u64 v[36:37], v[36:37], 0, s[100:101]
	global_load_ushort v150, v[36:37], off offset:1024
	global_load_ushort v151, v[36:37], off
	v_lshl_add_u64 v[36:37], v[36:37], 0, s[100:101]
	global_load_ushort v152, v[36:37], off offset:1024
	global_load_ushort v153, v[36:37], off
	v_lshl_add_u64 v[36:37], v[36:37], 0, s[100:101]
	global_load_ushort v155, v[36:37], off offset:1024
	global_load_ushort v154, v[36:37], off
	v_lshl_add_u64 v[36:37], v[36:37], 0, s[100:101]
	global_load_ushort v156, v[36:37], off offset:1024
	global_load_ushort v157, v[36:37], off
	v_lshl_add_u64 v[36:37], v[36:37], 0, s[100:101]
	global_load_ushort v158, v[36:37], off offset:1024
	global_load_ushort v159, v[36:37], off
	s_waitcnt vmcnt(0)
	s_cbranch_scc1 .LBB0_371
	v_lshlrev_b32_e32 v35, 16, v100
	v_mul_f32_e32 v35, 0xbfb8aa3b, v35
	v_exp_f32_e32 v35, v35
	v_lshlrev_b32_e32 v34, 16, v101
	v_add_f32_e32 v35, 1.0, v35
	v_rcp_f32_e32 v35, v35
	s_nop 0
	v_mul_f32_e32 v93, v35, v34
.LBB0_371:
	v_cndmask_b32_e64 v34, 0, 1, s[0:1]
	v_cmp_ne_u32_e64 s[8:9], 1, v34
	s_andn2_b64 vcc, exec, s[0:1]
	s_cbranch_vccnz .LBB0_373
	v_lshlrev_b32_e32 v35, 16, v102
	v_mul_f32_e32 v35, 0xbfb8aa3b, v35
	v_exp_f32_e32 v35, v35
	v_lshlrev_b32_e32 v34, 16, v103
	v_add_f32_e32 v35, 1.0, v35
	v_rcp_f32_e32 v35, v35
	s_nop 0
	v_mul_f32_e32 v90, v35, v34
.LBB0_373:
	v_mov_b32_e32 v86, 0
	s_and_b64 vcc, exec, s[8:9]
	v_mov_b32_e32 v91, 0
	s_cbranch_vccnz .LBB0_375
	v_lshlrev_b32_e32 v35, 16, v104
	v_mul_f32_e32 v35, 0xbfb8aa3b, v35
	v_exp_f32_e32 v35, v35
	v_lshlrev_b32_e32 v34, 16, v105
	v_add_f32_e32 v35, 1.0, v35
	v_rcp_f32_e32 v35, v35
	s_nop 0
	v_mul_f32_e32 v91, v35, v34
.LBB0_375:
	s_and_b64 vcc, exec, s[8:9]
	s_cbranch_vccnz .LBB0_377
	v_lshlrev_b32_e32 v36, 16, v106
	v_lshlrev_b32_e32 v34, 16, v107
	v_mul_f32_e32 v34, 0xbfb8aa3b, v34
	v_exp_f32_e32 v34, v34
	s_nop 0
	v_add_f32_e32 v34, 1.0, v34
	v_rcp_f32_e32 v34, v34
	s_nop 0
	v_mul_f32_e32 v86, v34, v36
.LBB0_377:
	v_mov_b32_e32 v84, 0
	s_and_b64 vcc, exec, s[8:9]
	v_mov_b32_e32 v85, 0
	s_cbranch_vccnz .LBB0_379
	v_lshlrev_b32_e32 v35, 16, v108
	v_mul_f32_e32 v35, 0xbfb8aa3b, v35
	v_exp_f32_e32 v35, v35
	v_lshlrev_b32_e32 v34, 16, v109
	v_add_f32_e32 v35, 1.0, v35
	v_rcp_f32_e32 v35, v35
	s_nop 0
	v_mul_f32_e32 v85, v35, v34
.LBB0_379:
	s_and_b64 vcc, exec, s[8:9]
	s_cbranch_vccnz .LBB0_381
	v_lshlrev_b32_e32 v35, 16, v110
	v_mul_f32_e32 v35, 0xbfb8aa3b, v35
	v_exp_f32_e32 v35, v35
	v_lshlrev_b32_e32 v34, 16, v111
	v_add_f32_e32 v35, 1.0, v35
	v_rcp_f32_e32 v35, v35
	s_nop 0
	v_mul_f32_e32 v84, v35, v34
.LBB0_381:
	v_mov_b32_e32 v82, 0
	s_and_b64 vcc, exec, s[8:9]
	v_mov_b32_e32 v83, 0
	s_cbranch_vccnz .LBB0_383
	v_lshlrev_b32_e32 v35, 16, v112
	v_mul_f32_e32 v35, 0xbfb8aa3b, v35
	v_exp_f32_e32 v35, v35
	v_lshlrev_b32_e32 v34, 16, v113
	v_add_f32_e32 v35, 1.0, v35
	v_rcp_f32_e32 v35, v35
	s_nop 0
	v_mul_f32_e32 v83, v35, v34
.LBB0_383:
	s_and_b64 vcc, exec, s[8:9]
	s_cbranch_vccnz .LBB0_385
	v_lshlrev_b32_e32 v36, 16, v114
	v_lshlrev_b32_e32 v34, 16, v115
	v_mul_f32_e32 v34, 0xbfb8aa3b, v34
	v_exp_f32_e32 v34, v34
	s_nop 0
	v_add_f32_e32 v34, 1.0, v34
	v_rcp_f32_e32 v34, v34
	s_nop 0
	v_mul_f32_e32 v82, v34, v36
.LBB0_385:
	v_mov_b32_e32 v80, 0
	s_and_b64 vcc, exec, s[8:9]
	v_mov_b32_e32 v81, 0
	s_cbranch_vccnz .LBB0_387
	v_lshlrev_b32_e32 v35, 16, v116
	v_mul_f32_e32 v35, 0xbfb8aa3b, v35
	v_exp_f32_e32 v35, v35
	v_lshlrev_b32_e32 v34, 16, v117
	v_add_f32_e32 v35, 1.0, v35
	v_rcp_f32_e32 v35, v35
	s_nop 0
	v_mul_f32_e32 v81, v35, v34
.LBB0_387:
	s_and_b64 vcc, exec, s[8:9]
	s_cbranch_vccnz .LBB0_389
	v_lshlrev_b32_e32 v35, 16, v118
	v_mul_f32_e32 v35, 0xbfb8aa3b, v35
	v_exp_f32_e32 v35, v35
	v_lshlrev_b32_e32 v34, 16, v119
	v_add_f32_e32 v35, 1.0, v35
	v_rcp_f32_e32 v35, v35
	s_nop 0
	v_mul_f32_e32 v80, v35, v34
.LBB0_389:
	v_mov_b32_e32 v78, 0
	s_and_b64 vcc, exec, s[8:9]
	v_mov_b32_e32 v79, 0
	s_cbranch_vccnz .LBB0_391
	v_lshlrev_b32_e32 v35, 16, v120
	v_mul_f32_e32 v35, 0xbfb8aa3b, v35
	v_exp_f32_e32 v35, v35
	v_lshlrev_b32_e32 v34, 16, v121
	v_add_f32_e32 v35, 1.0, v35
	v_rcp_f32_e32 v35, v35
	s_nop 0
	v_mul_f32_e32 v79, v35, v34
; __device__ __forceinline__ float bf2f(unsigned short b) { return __uint_as_float((unsigned)b << 16); }
; __device__ __forceinline__ float fexp2(float x) { return __builtin_amdgcn_exp2f(x); }
; __device__ __forceinline__ float frcp(float x) { return __builtin_amdgcn_rcpf(x); }
; __device__ __forceinline__ float sigmoidf_(float x) { return frcp(1.0f + fexp2(-1.4426950408889634f * x)); }
; __device__ __forceinline__ void conv_item(LAS unsigned char* lds, const bf16* PROJ, bf16* MIX, const float* cw, const float* cb, const float* lg, const float* lb, int item, int tid) {
;     ...
;     for (int i = 0; i < 62; ++i) { float hv = 0.f;
;         if (pos0 - 30 + i >= 0) { const bf16* rp = PROJ + (size_t)(row0 - 30 + i) * NPROJ; const float a = bf2f(rp[1536 + c]), g = bf2f(rp[2048 + c]); hv = a * sigmoidf_(g); }
;         hw[i] = hv; }
.LBB0_391:
	s_and_b64 vcc, exec, s[8:9]
	s_cbranch_vccnz .LBB0_393
	v_lshlrev_b32_e32 v36, 16, v122
	v_lshlrev_b32_e32 v34, 16, v123
	v_mul_f32_e32 v34, 0xbfb8aa3b, v34
	v_exp_f32_e32 v34, v34
	s_nop 0
	v_add_f32_e32 v34, 1.0, v34
	v_rcp_f32_e32 v34, v34
	s_nop 0
	v_mul_f32_e32 v78, v34, v36
.LBB0_393:
	v_mov_b32_e32 v70, 0
	s_and_b64 vcc, exec, s[8:9]
	v_mov_b32_e32 v77, 0
	s_cbranch_vccnz .LBB0_395
	v_lshlrev_b32_e32 v35, 16, v124
	v_mul_f32_e32 v35, 0xbfb8aa3b, v35
	v_exp_f32_e32 v35, v35
	v_lshlrev_b32_e32 v34, 16, v125
	v_add_f32_e32 v35, 1.0, v35
	v_rcp_f32_e32 v35, v35
	s_nop 0
	v_mul_f32_e32 v77, v35, v34
.LBB0_395:
	s_and_b64 vcc, exec, s[8:9]
	s_cbranch_vccnz .LBB0_397
	v_lshlrev_b32_e32 v35, 16, v126
	v_mul_f32_e32 v35, 0xbfb8aa3b, v35
	v_exp_f32_e32 v35, v35
	v_lshlrev_b32_e32 v34, 16, v127
	v_add_f32_e32 v35, 1.0, v35
	v_rcp_f32_e32 v35, v35
	s_nop 0
	v_mul_f32_e32 v70, v35, v34
.LBB0_397:
	v_mov_b32_e32 v64, 0
	s_and_b64 vcc, exec, s[8:9]
	v_mov_b32_e32 v69, 0
	s_cbranch_vccnz .LBB0_399
	v_lshlrev_b32_e32 v35, 16, v128
	v_mul_f32_e32 v35, 0xbfb8aa3b, v35
	v_exp_f32_e32 v35, v35
	v_lshlrev_b32_e32 v34, 16, v129
	v_add_f32_e32 v35, 1.0, v35
	v_rcp_f32_e32 v35, v35
	s_nop 0
	v_mul_f32_e32 v69, v35, v34
.LBB0_399:
	s_and_b64 vcc, exec, s[8:9]
	s_cbranch_vccnz .LBB0_401
	v_lshlrev_b32_e32 v36, 16, v130
	v_lshlrev_b32_e32 v34, 16, v131
	v_mul_f32_e32 v34, 0xbfb8aa3b, v34
	v_exp_f32_e32 v34, v34
	s_nop 0
	v_add_f32_e32 v34, 1.0, v34
	v_rcp_f32_e32 v34, v34
	s_nop 0
	v_mul_f32_e32 v64, v34, v36
.LBB0_401:
	v_mov_b32_e32 v55, 0
	s_and_b64 vcc, exec, s[8:9]
	v_mov_b32_e32 v62, 0
	s_cbranch_vccnz .LBB0_403
	v_lshlrev_b32_e32 v35, 16, v132
	v_mul_f32_e32 v35, 0xbfb8aa3b, v35
	v_exp_f32_e32 v35, v35
	v_lshlrev_b32_e32 v34, 16, v133
	v_add_f32_e32 v35, 1.0, v35
	v_rcp_f32_e32 v35, v35
	s_nop 0
	v_mul_f32_e32 v62, v35, v34
.LBB0_403:
	s_and_b64 vcc, exec, s[8:9]
	s_cbranch_vccnz .LBB0_405
	v_lshlrev_b32_e32 v35, 16, v134
	v_mul_f32_e32 v35, 0xbfb8aa3b, v35
	v_exp_f32_e32 v35, v35
	v_lshlrev_b32_e32 v34, 16, v135
	v_add_f32_e32 v35, 1.0, v35
	v_rcp_f32_e32 v35, v35
	s_nop 0
	v_mul_f32_e32 v55, v35, v34
.LBB0_405:
	v_mov_b32_e32 v52, 0
	s_and_b64 vcc, exec, s[8:9]
	v_mov_b32_e32 v54, 0
	s_cbranch_vccnz .LBB0_407
	v_lshlrev_b32_e32 v35, 16, v136
	v_mul_f32_e32 v35, 0xbfb8aa3b, v35
	v_exp_f32_e32 v35, v35
	v_lshlrev_b32_e32 v34, 16, v137
	v_add_f32_e32 v35, 1.0, v35
	v_rcp_f32_e32 v35, v35
	s_nop 0
	v_mul_f32_e32 v54, v35, v34
.LBB0_407:
	s_and_b64 vcc, exec, s[8:9]
	s_cbranch_vccnz .LBB0_409
	v_lshlrev_b32_e32 v36, 16, v138
	v_lshlrev_b32_e32 v34, 16, v139
	v_mul_f32_e32 v34, 0xbfb8aa3b, v34
	v_exp_f32_e32 v34, v34
	s_nop 0
	v_add_f32_e32 v34, 1.0, v34
	v_rcp_f32_e32 v34, v34
	s_nop 0
	v_mul_f32_e32 v52, v34, v36
.LBB0_409:
	v_mov_b32_e32 v50, 0
	s_and_b64 vcc, exec, s[8:9]
	v_mov_b32_e32 v51, 0
	s_cbranch_vccnz .LBB0_411
	v_lshlrev_b32_e32 v35, 16, v140
	v_mul_f32_e32 v35, 0xbfb8aa3b, v35
	v_exp_f32_e32 v35, v35
	v_lshlrev_b32_e32 v34, 16, v141
	v_add_f32_e32 v35, 1.0, v35
	v_rcp_f32_e32 v35, v35
	s_nop 0
	v_mul_f32_e32 v51, v35, v34
.LBB0_411:
	s_and_b64 vcc, exec, s[8:9]
	s_cbranch_vccnz .LBB0_413
	v_lshlrev_b32_e32 v35, 16, v142
	v_mul_f32_e32 v35, 0xbfb8aa3b, v35
	v_exp_f32_e32 v35, v35
	v_lshlrev_b32_e32 v34, 16, v143
	v_add_f32_e32 v35, 1.0, v35
	v_rcp_f32_e32 v35, v35
	s_nop 0
	v_mul_f32_e32 v50, v35, v34
.LBB0_413:
	v_mov_b32_e32 v46, 0
	s_and_b64 vcc, exec, s[8:9]
	v_mov_b32_e32 v49, 0
	s_cbranch_vccnz .LBB0_415
	v_lshlrev_b32_e32 v35, 16, v144
	v_mul_f32_e32 v35, 0xbfb8aa3b, v35
	v_exp_f32_e32 v35, v35
	v_lshlrev_b32_e32 v34, 16, v145
	v_add_f32_e32 v35, 1.0, v35
	v_rcp_f32_e32 v35, v35
	s_nop 0
	v_mul_f32_e32 v49, v35, v34
.LBB0_415:
	s_and_b64 vcc, exec, s[8:9]
	s_cbranch_vccnz .LBB0_417
	v_lshlrev_b32_e32 v36, 16, v146
	v_lshlrev_b32_e32 v34, 16, v147
	v_mul_f32_e32 v34, 0xbfb8aa3b, v34
	v_exp_f32_e32 v34, v34
	s_nop 0
	v_add_f32_e32 v34, 1.0, v34
	v_rcp_f32_e32 v34, v34
	s_nop 0
	v_mul_f32_e32 v46, v34, v36
.LBB0_417:
	v_mov_b32_e32 v44, 0
	s_and_b64 vcc, exec, s[8:9]
	v_mov_b32_e32 v45, 0
	s_cbranch_vccnz .LBB0_419
	v_lshlrev_b32_e32 v35, 16, v148
	v_mul_f32_e32 v35, 0xbfb8aa3b, v35
	v_exp_f32_e32 v35, v35
	v_lshlrev_b32_e32 v34, 16, v149
	v_add_f32_e32 v35, 1.0, v35
	v_rcp_f32_e32 v35, v35
	s_nop 0
	v_mul_f32_e32 v45, v35, v34
.LBB0_419:
	s_and_b64 vcc, exec, s[8:9]
	s_cbranch_vccnz .LBB0_421
	v_lshlrev_b32_e32 v35, 16, v150
	v_mul_f32_e32 v35, 0xbfb8aa3b, v35
	v_exp_f32_e32 v35, v35
	v_lshlrev_b32_e32 v34, 16, v151
	v_add_f32_e32 v35, 1.0, v35
	v_rcp_f32_e32 v35, v35
	s_nop 0
	v_mul_f32_e32 v44, v35, v34
.LBB0_421:
	v_mov_b32_e32 v40, 0
	s_and_b64 vcc, exec, s[8:9]
	v_mov_b32_e32 v43, 0
	s_cbranch_vccnz .LBB0_423
	v_lshlrev_b32_e32 v35, 16, v152
	v_mul_f32_e32 v35, 0xbfb8aa3b, v35
	v_exp_f32_e32 v35, v35
	v_lshlrev_b32_e32 v34, 16, v153
	v_add_f32_e32 v35, 1.0, v35
	v_rcp_f32_e32 v35, v35
	s_nop 0
	v_mul_f32_e32 v43, v35, v34
.LBB0_423:
	s_and_b64 vcc, exec, s[8:9]
	s_cbranch_vccnz .LBB0_425
	v_lshlrev_b32_e32 v36, 16, v154
	v_lshlrev_b32_e32 v34, 16, v155
	v_mul_f32_e32 v34, 0xbfb8aa3b, v34
	v_exp_f32_e32 v34, v34
	s_nop 0
	v_add_f32_e32 v34, 1.0, v34
	v_rcp_f32_e32 v34, v34
	s_nop 0
	v_mul_f32_e32 v40, v34, v36
.LBB0_425:
	s_and_b64 vcc, exec, s[0:1]
	s_cbranch_vccz .LBB0_430
	v_lshlrev_b32_e32 v35, 16, v156
	v_mul_f32_e32 v35, 0xbfb8aa3b, v35
	v_exp_f32_e32 v35, v35
	v_lshlrev_b32_e32 v34, 16, v157
	v_add_f32_e32 v35, 1.0, v35
	v_rcp_f32_e32 v35, v35
	s_nop 0
	v_mul_f32_e32 v41, v35, v34
	s_cbranch_execnz .LBB0_428

; __device__ __forceinline__ float bf2f(unsigned short b) { return __uint_as_float((unsigned)b << 16); }
; __device__ __forceinline__ float sigmoidf_(float x) { return frcp(1.0f + fexp2(-1.4426950408889634f * x)); }
; __device__ __forceinline__ void conv_item(LAS unsigned char* lds, const bf16* PROJ, bf16* MIX, const float* cw, const float* cb, const float* lg, const float* lb, int item, int tid) {
;     ...
;     for (int i = 0; i < 62; ++i) { float hv = 0.f;
;         if (pos0 - 30 + i >= 0) { const bf16* rp = PROJ + (size_t)(row0 - 30 + i) * NPROJ; const float a = bf2f(rp[1536 + c]), g = bf2f(rp[2048 + c]); hv = a * sigmoidf_(g); }
;         hw[i] = hv; }
.LBB0_428:
	s_and_b64 vcc, exec, s[8:9]
	v_lshl_add_u64 v[2:3], s[82:83], 1, v[2:3]
	s_cbranch_vccnz .LBB0_431
	v_lshlrev_b32_e32 v34, 16, v158
	v_mul_f32_e32 v34, 0xbfb8aa3b, v34
	v_exp_f32_e32 v34, v34
	v_lshlrev_b32_e32 v35, 16, v159
	v_add_f32_e32 v34, 1.0, v34
	v_rcp_f32_e32 v34, v34
	s_nop 0
	v_mul_f32_e32 v38, v34, v35
	s_branch .LBB0_432
